# GLU item: both epilogue bias loads issued ahead of the second weight batch (no full wait behind the first half's stores)
# baseline (speedup 1.0000x reference)
; __device__ __forceinline__ void glu_item(Frame& F, const Args& AR, int l, int item) {
;     ...
;     bf16x8v b1[8][2]; wave_bfrags<K>(Bt, 1, b1, F.lane);
;     __syncthreads();
;     f32x4 acc[MT][2];
; #pragma unroll
;     for (int m = 0; m < MT; ++m)
; #pragma unroll
;         for (int n = 0; n < 2; ++n) acc[m][n] = (f32x4){0.f, 0.f, 0.f, 0.f};
;     { wave_mma_batch<K, MT>(at, LDA, 0, b0, acc, F.lane); wave_mma_batch<K, MT>(at, LDA, 1, b1, acc, F.lane); }
;     ...
;     for (int n = 0; n < 2; ++n) { const int col = colw + n * 16 + 4 * fq; const f32x4 bias = *(const f32x4*)(AR.in[I_GLUB] + l * 512 + col);
.LBB0_1679:
	s_or_b64 exec, exec, s[6:7]
	s_waitcnt vmcnt(0)
	v_or_b32_e32 v208, s4, v141
	v_ashrrev_i32_e32 v209, 31, v208
	v_lshl_add_u64 v[208:209], v[208:209], 2, s[0:1]
	global_load_dwordx4 v[200:203], v[208:209], off
	global_load_dwordx4 v[204:207], v[208:209], off offset:64
	v_mov_b32_e32 v137, v195
	v_lshl_add_u64 v[32:33], v[6:7], 0, v[136:137]
	v_add_u32_e32 v137, v139, v140
	global_load_dwordx4 v[66:69], v[30:31], off offset:512
	global_load_dwordx4 v[70:73], v[32:33], off offset:512
	global_load_dwordx4 v[50:53], v[30:31], off offset:576
	global_load_dwordx4 v[54:57], v[32:33], off offset:576
	global_load_dwordx4 v[42:45], v[30:31], off offset:640
	global_load_dwordx4 v[46:49], v[32:33], off offset:640
	global_load_dwordx4 v[34:37], v[30:31], off offset:704
	global_load_dwordx4 v[38:41], v[32:33], off offset:704
	global_load_dwordx4 v[22:25], v[30:31], off offset:768
	global_load_dwordx4 v[26:29], v[32:33], off offset:768
	global_load_dwordx4 v[14:17], v[30:31], off offset:832
	global_load_dwordx4 v[18:21], v[32:33], off offset:832
	global_load_dwordx4 v[6:9], v[30:31], off offset:896
	global_load_dwordx4 v[10:13], v[32:33], off offset:896
	global_load_dwordx4 v[2:5], v[30:31], off offset:960
	s_nop 0
	global_load_dwordx4 v[30:33], v[32:33], off offset:960
	s_waitcnt lgkmcnt(0)
	s_barrier
	ds_read_b128 v[148:151], v137
	ds_read_b128 v[156:159], v137 offset:16640
	ds_read_b128 v[164:167], v137 offset:33280
	ds_read_b128 v[172:175], v137 offset:49920
	ds_read_b128 v[180:183], v147
	s_waitcnt lgkmcnt(4)
	v_mfma_f32_16x16x32_bf16 v[152:155], v[122:125], v[148:151], 0
	v_mfma_f32_16x16x32_bf16 v[148:151], v[126:129], v[148:151], 0
	s_waitcnt lgkmcnt(3)
	v_mfma_f32_16x16x32_bf16 v[160:163], v[122:125], v[156:159], 0
	v_mfma_f32_16x16x32_bf16 v[156:159], v[126:129], v[156:159], 0
	s_waitcnt lgkmcnt(2)
	v_mfma_f32_16x16x32_bf16 v[168:171], v[122:125], v[164:167], 0
	v_mfma_f32_16x16x32_bf16 v[164:167], v[126:129], v[164:167], 0
	s_waitcnt lgkmcnt(1)
	v_mfma_f32_16x16x32_bf16 v[176:179], v[122:125], v[172:175], 0
	v_mfma_f32_16x16x32_bf16 v[172:175], v[126:129], v[172:175], 0
	s_waitcnt lgkmcnt(0)
	v_mfma_f32_16x16x32_bf16 v[122:125], v[122:125], v[180:183], 0
	v_mfma_f32_16x16x32_bf16 v[126:129], v[126:129], v[180:183], 0
	ds_read_b128 v[180:183], v137 offset:64
	s_waitcnt lgkmcnt(0)
	v_mfma_f32_16x16x32_bf16 v[152:155], v[114:117], v[180:183], v[152:155]
	v_mfma_f32_16x16x32_bf16 v[148:151], v[118:121], v[180:183], v[148:151]
	ds_read_b128 v[180:183], v137 offset:16704
	s_waitcnt lgkmcnt(0)
	v_mfma_f32_16x16x32_bf16 v[160:163], v[114:117], v[180:183], v[160:163]
	v_mfma_f32_16x16x32_bf16 v[156:159], v[118:121], v[180:183], v[156:159]
	ds_read_b128 v[180:183], v137 offset:33344
	s_waitcnt lgkmcnt(0)
	v_mfma_f32_16x16x32_bf16 v[168:171], v[114:117], v[180:183], v[168:171]
	v_mfma_f32_16x16x32_bf16 v[164:167], v[118:121], v[180:183], v[164:167]
	ds_read_b128 v[180:183], v137 offset:49984
	s_waitcnt lgkmcnt(0)
	v_mfma_f32_16x16x32_bf16 v[176:179], v[114:117], v[180:183], v[176:179]
	v_mfma_f32_16x16x32_bf16 v[172:175], v[118:121], v[180:183], v[172:175]
	ds_read_b128 v[180:183], v147 offset:64
	s_waitcnt lgkmcnt(0)
	v_mfma_f32_16x16x32_bf16 v[114:117], v[114:117], v[180:183], v[122:125]
	s_nop 2
	ds_read_b128 v[122:125], v137 offset:128
	v_mfma_f32_16x16x32_bf16 v[118:121], v[118:121], v[180:183], v[126:129]
	s_waitcnt lgkmcnt(0)
	v_mfma_f32_16x16x32_bf16 v[126:129], v[106:109], v[122:125], v[152:155]
	v_mfma_f32_16x16x32_bf16 v[122:125], v[110:113], v[122:125], v[148:151]
	s_nop 2
	ds_read_b128 v[148:151], v137 offset:16768
	s_waitcnt lgkmcnt(0)
	v_mfma_f32_16x16x32_bf16 v[152:155], v[106:109], v[148:151], v[160:163]
	v_mfma_f32_16x16x32_bf16 v[148:151], v[110:113], v[148:151], v[156:159]
	s_nop 2
	ds_read_b128 v[156:159], v137 offset:33408
	s_waitcnt lgkmcnt(0)
	v_mfma_f32_16x16x32_bf16 v[160:163], v[106:109], v[156:159], v[168:171]
	v_mfma_f32_16x16x32_bf16 v[156:159], v[110:113], v[156:159], v[164:167]
	s_nop 2
	ds_read_b128 v[164:167], v137 offset:50048
	s_waitcnt lgkmcnt(0)
	v_mfma_f32_16x16x32_bf16 v[168:171], v[106:109], v[164:167], v[176:179]
	v_mfma_f32_16x16x32_bf16 v[164:167], v[110:113], v[164:167], v[172:175]
	s_nop 2
	ds_read_b128 v[172:175], v147 offset:128
	s_waitcnt lgkmcnt(0)
	v_mfma_f32_16x16x32_bf16 v[106:109], v[106:109], v[172:175], v[114:117]
	s_nop 2
	ds_read_b128 v[114:117], v137 offset:192
	v_mfma_f32_16x16x32_bf16 v[110:113], v[110:113], v[172:175], v[118:121]
	s_waitcnt lgkmcnt(0)
	v_mfma_f32_16x16x32_bf16 v[118:121], v[98:101], v[114:117], v[126:129]
	v_mfma_f32_16x16x32_bf16 v[114:117], v[102:105], v[114:117], v[122:125]
	s_nop 2
	ds_read_b128 v[122:125], v137 offset:16832
	s_waitcnt lgkmcnt(0)
	v_mfma_f32_16x16x32_bf16 v[126:129], v[98:101], v[122:125], v[152:155]
	v_mfma_f32_16x16x32_bf16 v[122:125], v[102:105], v[122:125], v[148:151]
	s_nop 2
	ds_read_b128 v[148:151], v137 offset:33472
	s_waitcnt lgkmcnt(0)
	v_mfma_f32_16x16x32_bf16 v[152:155], v[98:101], v[148:151], v[160:163]
	v_mfma_f32_16x16x32_bf16 v[148:151], v[102:105], v[148:151], v[156:159]
	s_nop 2
	ds_read_b128 v[156:159], v137 offset:50112
	s_waitcnt lgkmcnt(0)
	v_mfma_f32_16x16x32_bf16 v[160:163], v[98:101], v[156:159], v[168:171]
	v_mfma_f32_16x16x32_bf16 v[156:159], v[102:105], v[156:159], v[164:167]
	s_nop 2
	ds_read_b128 v[164:167], v147 offset:192
	s_waitcnt lgkmcnt(0)
	v_mfma_f32_16x16x32_bf16 v[98:101], v[98:101], v[164:167], v[106:109]
	s_nop 2
	ds_read_b128 v[106:109], v137 offset:256
	v_mfma_f32_16x16x32_bf16 v[102:105], v[102:105], v[164:167], v[110:113]
	s_waitcnt lgkmcnt(0)
; #define LAS __attribute__((address_space(3)))
; template <int K, int MT> __device__ __forceinline__ void wave_mma_batch(const LAS unsigned char* a_lds, int lda, int kb, const bf16x8v (&bfr)[8][2], f32x4 (&acc)[MT][2], int lane) {
;     const int fr = lane & 15, fq = lane >> 4;
; #pragma unroll
;     for (int ks = 0; ks < 8; ++ks)
; #pragma unroll
;         for (int m = 0; m < MT; ++m) { const bf16x8v af = *(const LAS bf16x8v*)(a_lds + (m * 16 + fr) * lda + (kb * 256 + ks * 32 + 8 * fq) * 2);
; #pragma unroll
;             for (int n = 0; n < 2; ++n) acc[m][n] = __builtin_amdgcn_mfma_f32_16x16x32_bf16(bfr[ks][n], af, acc[m][n], 0, 0, 0); }
; }
	v_mfma_f32_16x16x32_bf16 v[110:113], v[90:93], v[106:109], v[118:121]
	v_mfma_f32_16x16x32_bf16 v[106:109], v[94:97], v[106:109], v[114:117]
	s_nop 2
	ds_read_b128 v[114:117], v137 offset:16896
	s_waitcnt lgkmcnt(0)
	v_mfma_f32_16x16x32_bf16 v[118:121], v[90:93], v[114:117], v[126:129]
	v_mfma_f32_16x16x32_bf16 v[114:117], v[94:97], v[114:117], v[122:125]
	s_nop 2
	ds_read_b128 v[122:125], v137 offset:33536
	s_waitcnt lgkmcnt(0)
	v_mfma_f32_16x16x32_bf16 v[126:129], v[90:93], v[122:125], v[152:155]
	v_mfma_f32_16x16x32_bf16 v[122:125], v[94:97], v[122:125], v[148:151]
	s_nop 2
	ds_read_b128 v[148:151], v137 offset:50176
	s_waitcnt lgkmcnt(0)
	v_mfma_f32_16x16x32_bf16 v[152:155], v[90:93], v[148:151], v[160:163]
	v_mfma_f32_16x16x32_bf16 v[148:151], v[94:97], v[148:151], v[156:159]
	s_nop 2
	ds_read_b128 v[156:159], v147 offset:256
	s_waitcnt lgkmcnt(0)
	v_mfma_f32_16x16x32_bf16 v[90:93], v[90:93], v[156:159], v[98:101]
	s_nop 2
	ds_read_b128 v[98:101], v137 offset:320
	v_mfma_f32_16x16x32_bf16 v[94:97], v[94:97], v[156:159], v[102:105]
	s_waitcnt lgkmcnt(0)
	v_mfma_f32_16x16x32_bf16 v[102:105], v[82:85], v[98:101], v[110:113]
	v_mfma_f32_16x16x32_bf16 v[98:101], v[86:89], v[98:101], v[106:109]
	s_nop 2
	ds_read_b128 v[106:109], v137 offset:16960
	s_waitcnt lgkmcnt(0)
	v_mfma_f32_16x16x32_bf16 v[110:113], v[82:85], v[106:109], v[118:121]
	v_mfma_f32_16x16x32_bf16 v[106:109], v[86:89], v[106:109], v[114:117]
	s_nop 2
	ds_read_b128 v[114:117], v137 offset:33600
	s_waitcnt lgkmcnt(0)
	v_mfma_f32_16x16x32_bf16 v[118:121], v[82:85], v[114:117], v[126:129]
	v_mfma_f32_16x16x32_bf16 v[114:117], v[86:89], v[114:117], v[122:125]
	s_nop 2
	ds_read_b128 v[122:125], v137 offset:50240
	s_waitcnt lgkmcnt(0)
	v_mfma_f32_16x16x32_bf16 v[126:129], v[82:85], v[122:125], v[152:155]
	v_mfma_f32_16x16x32_bf16 v[122:125], v[86:89], v[122:125], v[148:151]
	s_nop 2
	ds_read_b128 v[148:151], v147 offset:320
	s_waitcnt lgkmcnt(0)
	v_mfma_f32_16x16x32_bf16 v[82:85], v[82:85], v[148:151], v[90:93]
	s_nop 2
	ds_read_b128 v[90:93], v137 offset:384
	v_mfma_f32_16x16x32_bf16 v[86:89], v[86:89], v[148:151], v[94:97]
	s_waitcnt lgkmcnt(0)
	v_mfma_f32_16x16x32_bf16 v[94:97], v[74:77], v[90:93], v[102:105]
	v_mfma_f32_16x16x32_bf16 v[90:93], v[78:81], v[90:93], v[98:101]
	s_nop 2
	ds_read_b128 v[98:101], v137 offset:17024
	s_waitcnt lgkmcnt(0)
	v_mfma_f32_16x16x32_bf16 v[102:105], v[74:77], v[98:101], v[110:113]
	v_mfma_f32_16x16x32_bf16 v[98:101], v[78:81], v[98:101], v[106:109]
	s_nop 2
	ds_read_b128 v[106:109], v137 offset:33664
	s_waitcnt lgkmcnt(0)
	v_mfma_f32_16x16x32_bf16 v[110:113], v[74:77], v[106:109], v[118:121]
	v_mfma_f32_16x16x32_bf16 v[106:109], v[78:81], v[106:109], v[114:117]
	s_nop 2
	ds_read_b128 v[114:117], v137 offset:50304
	s_waitcnt lgkmcnt(0)
	v_mfma_f32_16x16x32_bf16 v[118:121], v[74:77], v[114:117], v[126:129]
	v_mfma_f32_16x16x32_bf16 v[114:117], v[78:81], v[114:117], v[122:125]
	s_nop 2
	ds_read_b128 v[122:125], v147 offset:384
	s_waitcnt lgkmcnt(0)
	v_mfma_f32_16x16x32_bf16 v[74:77], v[74:77], v[122:125], v[82:85]
	s_nop 2
	ds_read_b128 v[82:85], v137 offset:448
	v_mfma_f32_16x16x32_bf16 v[78:81], v[78:81], v[122:125], v[86:89]
	s_waitcnt lgkmcnt(0)
	v_mfma_f32_16x16x32_bf16 v[86:89], v[58:61], v[82:85], v[94:97]
	v_mfma_f32_16x16x32_bf16 v[82:85], v[62:65], v[82:85], v[90:93]
	s_nop 2
	ds_read_b128 v[90:93], v137 offset:17088
	s_waitcnt lgkmcnt(0)
	v_mfma_f32_16x16x32_bf16 v[94:97], v[58:61], v[90:93], v[102:105]
	v_mfma_f32_16x16x32_bf16 v[90:93], v[62:65], v[90:93], v[98:101]
	s_nop 2
	ds_read_b128 v[98:101], v137 offset:33728
	s_waitcnt lgkmcnt(0)
	v_mfma_f32_16x16x32_bf16 v[102:105], v[58:61], v[98:101], v[110:113]
	v_mfma_f32_16x16x32_bf16 v[98:101], v[62:65], v[98:101], v[106:109]
	s_nop 2
	ds_read_b128 v[106:109], v137 offset:50368
	s_waitcnt lgkmcnt(0)
	v_mfma_f32_16x16x32_bf16 v[110:113], v[58:61], v[106:109], v[118:121]
	v_mfma_f32_16x16x32_bf16 v[106:109], v[62:65], v[106:109], v[114:117]
	s_nop 2
	ds_read_b128 v[114:117], v147 offset:448
	s_waitcnt lgkmcnt(0)
	v_mfma_f32_16x16x32_bf16 v[58:61], v[58:61], v[114:117], v[74:77]
	s_nop 2
	ds_read_b128 v[74:77], v137 offset:512
	v_mfma_f32_16x16x32_bf16 v[62:65], v[62:65], v[114:117], v[78:81]
	s_waitcnt vmcnt(15) lgkmcnt(0)
	v_mfma_f32_16x16x32_bf16 v[78:81], v[66:69], v[74:77], v[86:89]
	s_waitcnt vmcnt(14)
	v_mfma_f32_16x16x32_bf16 v[74:77], v[70:73], v[74:77], v[82:85]
	s_nop 2
	ds_read_b128 v[82:85], v137 offset:17152
	s_waitcnt lgkmcnt(0)
	v_mfma_f32_16x16x32_bf16 v[86:89], v[66:69], v[82:85], v[94:97]
	v_mfma_f32_16x16x32_bf16 v[82:85], v[70:73], v[82:85], v[90:93]
	s_nop 2
	ds_read_b128 v[90:93], v137 offset:33792
	s_waitcnt lgkmcnt(0)
	v_mfma_f32_16x16x32_bf16 v[94:97], v[66:69], v[90:93], v[102:105]
	v_mfma_f32_16x16x32_bf16 v[90:93], v[70:73], v[90:93], v[98:101]
	s_nop 2
	ds_read_b128 v[98:101], v137 offset:50432
	s_waitcnt lgkmcnt(0)
	v_mfma_f32_16x16x32_bf16 v[102:105], v[66:69], v[98:101], v[110:113]
	v_mfma_f32_16x16x32_bf16 v[98:101], v[70:73], v[98:101], v[106:109]
	s_nop 2
	ds_read_b128 v[106:109], v147 offset:512
	s_waitcnt lgkmcnt(0)
	v_mfma_f32_16x16x32_bf16 v[58:61], v[66:69], v[106:109], v[58:61]
	ds_read_b128 v[66:69], v137 offset:576
	v_mfma_f32_16x16x32_bf16 v[62:65], v[70:73], v[106:109], v[62:65]
	s_waitcnt vmcnt(13) lgkmcnt(0)
	v_mfma_f32_16x16x32_bf16 v[70:73], v[50:53], v[66:69], v[78:81]
	s_waitcnt vmcnt(12)
	v_mfma_f32_16x16x32_bf16 v[66:69], v[54:57], v[66:69], v[74:77]
	s_nop 2
	ds_read_b128 v[74:77], v137 offset:17216
	s_waitcnt lgkmcnt(0)
	v_mfma_f32_16x16x32_bf16 v[78:81], v[50:53], v[74:77], v[86:89]
	v_mfma_f32_16x16x32_bf16 v[74:77], v[54:57], v[74:77], v[82:85]
	s_nop 2
	ds_read_b128 v[82:85], v137 offset:33856
	s_waitcnt lgkmcnt(0)
; #define LAS __attribute__((address_space(3)))
; template <int K, int MT> __device__ __forceinline__ void wave_mma_batch(const LAS unsigned char* a_lds, int lda, int kb, const bf16x8v (&bfr)[8][2], f32x4 (&acc)[MT][2], int lane) {
;     const int fr = lane & 15, fq = lane >> 4;
; #pragma unroll
;     for (int ks = 0; ks < 8; ++ks)
; #pragma unroll
;         for (int m = 0; m < MT; ++m) { const bf16x8v af = *(const LAS bf16x8v*)(a_lds + (m * 16 + fr) * lda + (kb * 256 + ks * 32 + 8 * fq) * 2);
; #pragma unroll
;             for (int n = 0; n < 2; ++n) acc[m][n] = __builtin_amdgcn_mfma_f32_16x16x32_bf16(bfr[ks][n], af, acc[m][n], 0, 0, 0); }
; }
	v_mfma_f32_16x16x32_bf16 v[86:89], v[50:53], v[82:85], v[94:97]
	v_mfma_f32_16x16x32_bf16 v[82:85], v[54:57], v[82:85], v[90:93]
	s_nop 2
	ds_read_b128 v[90:93], v137 offset:50496
	s_waitcnt lgkmcnt(0)
	v_mfma_f32_16x16x32_bf16 v[94:97], v[50:53], v[90:93], v[102:105]
	v_mfma_f32_16x16x32_bf16 v[90:93], v[54:57], v[90:93], v[98:101]
	s_nop 2
	ds_read_b128 v[98:101], v147 offset:576
	s_waitcnt lgkmcnt(0)
	v_mfma_f32_16x16x32_bf16 v[50:53], v[50:53], v[98:101], v[58:61]
	s_nop 2
	ds_read_b128 v[58:61], v137 offset:640
	v_mfma_f32_16x16x32_bf16 v[54:57], v[54:57], v[98:101], v[62:65]
	s_waitcnt vmcnt(11) lgkmcnt(0)
	v_mfma_f32_16x16x32_bf16 v[62:65], v[42:45], v[58:61], v[70:73]
	s_waitcnt vmcnt(10)
	v_mfma_f32_16x16x32_bf16 v[58:61], v[46:49], v[58:61], v[66:69]
	s_nop 2
	ds_read_b128 v[66:69], v137 offset:17280
	s_waitcnt lgkmcnt(0)
	v_mfma_f32_16x16x32_bf16 v[70:73], v[42:45], v[66:69], v[78:81]
	v_mfma_f32_16x16x32_bf16 v[66:69], v[46:49], v[66:69], v[74:77]
	s_nop 2
	ds_read_b128 v[74:77], v137 offset:33920
	s_waitcnt lgkmcnt(0)
	v_mfma_f32_16x16x32_bf16 v[78:81], v[42:45], v[74:77], v[86:89]
	v_mfma_f32_16x16x32_bf16 v[74:77], v[46:49], v[74:77], v[82:85]
	s_nop 2
	ds_read_b128 v[82:85], v137 offset:50560
	s_waitcnt lgkmcnt(0)
	v_mfma_f32_16x16x32_bf16 v[86:89], v[42:45], v[82:85], v[94:97]
	v_mfma_f32_16x16x32_bf16 v[82:85], v[46:49], v[82:85], v[90:93]
	s_nop 2
	ds_read_b128 v[90:93], v147 offset:640
	s_waitcnt lgkmcnt(0)
	v_mfma_f32_16x16x32_bf16 v[42:45], v[42:45], v[90:93], v[50:53]
	s_nop 2
	ds_read_b128 v[50:53], v137 offset:704
	v_mfma_f32_16x16x32_bf16 v[46:49], v[46:49], v[90:93], v[54:57]
	s_waitcnt vmcnt(9) lgkmcnt(0)
	v_mfma_f32_16x16x32_bf16 v[54:57], v[34:37], v[50:53], v[62:65]
	s_waitcnt vmcnt(8)
	v_mfma_f32_16x16x32_bf16 v[50:53], v[38:41], v[50:53], v[58:61]
	s_nop 2
	ds_read_b128 v[58:61], v137 offset:17344
	s_waitcnt lgkmcnt(0)
	v_mfma_f32_16x16x32_bf16 v[62:65], v[34:37], v[58:61], v[70:73]
	v_mfma_f32_16x16x32_bf16 v[58:61], v[38:41], v[58:61], v[66:69]
	s_nop 2
	ds_read_b128 v[66:69], v137 offset:33984
	s_waitcnt lgkmcnt(0)
	v_mfma_f32_16x16x32_bf16 v[70:73], v[34:37], v[66:69], v[78:81]
	v_mfma_f32_16x16x32_bf16 v[66:69], v[38:41], v[66:69], v[74:77]
	s_nop 2
	ds_read_b128 v[74:77], v137 offset:50624
	s_waitcnt lgkmcnt(0)
	v_mfma_f32_16x16x32_bf16 v[78:81], v[34:37], v[74:77], v[86:89]
	v_mfma_f32_16x16x32_bf16 v[74:77], v[38:41], v[74:77], v[82:85]
	s_nop 2
	ds_read_b128 v[82:85], v147 offset:704
	s_waitcnt lgkmcnt(0)
	v_mfma_f32_16x16x32_bf16 v[34:37], v[34:37], v[82:85], v[42:45]
	s_nop 2
	ds_read_b128 v[42:45], v137 offset:768
	v_mfma_f32_16x16x32_bf16 v[38:41], v[38:41], v[82:85], v[46:49]
	s_waitcnt vmcnt(7) lgkmcnt(0)
	v_mfma_f32_16x16x32_bf16 v[46:49], v[22:25], v[42:45], v[54:57]
	s_waitcnt vmcnt(6)
	v_mfma_f32_16x16x32_bf16 v[42:45], v[26:29], v[42:45], v[50:53]
	s_nop 2
	ds_read_b128 v[50:53], v137 offset:17408
	s_waitcnt lgkmcnt(0)
	v_mfma_f32_16x16x32_bf16 v[54:57], v[22:25], v[50:53], v[62:65]
	v_mfma_f32_16x16x32_bf16 v[50:53], v[26:29], v[50:53], v[58:61]
	s_nop 2
	ds_read_b128 v[58:61], v137 offset:34048
	s_waitcnt lgkmcnt(0)
	v_mfma_f32_16x16x32_bf16 v[62:65], v[22:25], v[58:61], v[70:73]
	v_mfma_f32_16x16x32_bf16 v[58:61], v[26:29], v[58:61], v[66:69]
	s_nop 2
	ds_read_b128 v[66:69], v137 offset:50688
	s_waitcnt lgkmcnt(0)
	v_mfma_f32_16x16x32_bf16 v[70:73], v[22:25], v[66:69], v[78:81]
	v_mfma_f32_16x16x32_bf16 v[66:69], v[26:29], v[66:69], v[74:77]
	s_nop 2
	ds_read_b128 v[74:77], v147 offset:768
	s_waitcnt lgkmcnt(0)
	v_mfma_f32_16x16x32_bf16 v[22:25], v[22:25], v[74:77], v[34:37]
	s_nop 2
	ds_read_b128 v[34:37], v137 offset:832
	v_mfma_f32_16x16x32_bf16 v[26:29], v[26:29], v[74:77], v[38:41]
	s_waitcnt vmcnt(5) lgkmcnt(0)
	v_mfma_f32_16x16x32_bf16 v[38:41], v[14:17], v[34:37], v[46:49]
	s_waitcnt vmcnt(4)
	v_mfma_f32_16x16x32_bf16 v[34:37], v[18:21], v[34:37], v[42:45]
	s_nop 2
	ds_read_b128 v[42:45], v137 offset:17472
	s_waitcnt lgkmcnt(0)
	v_mfma_f32_16x16x32_bf16 v[46:49], v[14:17], v[42:45], v[54:57]
	v_mfma_f32_16x16x32_bf16 v[42:45], v[18:21], v[42:45], v[50:53]
	s_nop 2
	ds_read_b128 v[50:53], v137 offset:34112
	s_waitcnt lgkmcnt(0)
	v_mfma_f32_16x16x32_bf16 v[54:57], v[14:17], v[50:53], v[62:65]
	v_mfma_f32_16x16x32_bf16 v[50:53], v[18:21], v[50:53], v[58:61]
	s_nop 2
	ds_read_b128 v[58:61], v137 offset:50752
	s_waitcnt lgkmcnt(0)
	v_mfma_f32_16x16x32_bf16 v[62:65], v[14:17], v[58:61], v[70:73]
	v_mfma_f32_16x16x32_bf16 v[58:61], v[18:21], v[58:61], v[66:69]
	s_nop 2
	ds_read_b128 v[66:69], v147 offset:832
	s_waitcnt lgkmcnt(0)
	v_mfma_f32_16x16x32_bf16 v[14:17], v[14:17], v[66:69], v[22:25]
	s_nop 2
	ds_read_b128 v[22:25], v137 offset:896
	v_mfma_f32_16x16x32_bf16 v[18:21], v[18:21], v[66:69], v[26:29]
	s_waitcnt vmcnt(3) lgkmcnt(0)
	v_mfma_f32_16x16x32_bf16 v[26:29], v[6:9], v[22:25], v[38:41]
	s_waitcnt vmcnt(2)
	v_mfma_f32_16x16x32_bf16 v[22:25], v[10:13], v[22:25], v[34:37]
	s_nop 2
	ds_read_b128 v[34:37], v137 offset:17536
	s_waitcnt lgkmcnt(0)
	v_mfma_f32_16x16x32_bf16 v[38:41], v[6:9], v[34:37], v[46:49]
	v_mfma_f32_16x16x32_bf16 v[34:37], v[10:13], v[34:37], v[42:45]
	s_nop 2
	ds_read_b128 v[42:45], v137 offset:34176
	s_waitcnt lgkmcnt(0)
	v_mfma_f32_16x16x32_bf16 v[46:49], v[6:9], v[42:45], v[54:57]
	v_mfma_f32_16x16x32_bf16 v[50:53], v[10:13], v[42:45], v[50:53]
	ds_read_b128 v[42:45], v137 offset:50816
	s_waitcnt lgkmcnt(0)
	v_mfma_f32_16x16x32_bf16 v[54:57], v[6:9], v[42:45], v[62:65]
	v_mfma_f32_16x16x32_bf16 v[58:61], v[10:13], v[42:45], v[58:61]
	ds_read_b128 v[42:45], v147 offset:896
	s_waitcnt lgkmcnt(0)
; #define LAS __attribute__((address_space(3)))
; __device__ __forceinline__ unsigned pk2(float lo, float hi) { const f32x2cv v = {lo, hi}; return __builtin_bit_cast(unsigned, __builtin_convertvector(v, bf16x2cv)); }
; __device__ __forceinline__ float sigmoidf_(float x) { return __builtin_amdgcn_rcpf(1.0f + __expf(-x)); }
; __device__ __forceinline__ void glu_item(Frame& F, const Args& AR, int l, int item) {
;     ...
;     { wave_mma_batch<K, MT>(at, LDA, 0, b0, acc, F.lane); wave_mma_batch<K, MT>(at, LDA, 1, b1, acc, F.lane); }
;     const int fr = F.lane & 15, fq = F.lane >> 4;
; #pragma unroll
;     for (int n = 0; n < 2; ++n) { const int col = colw + n * 16 + 4 * fq; const f32x4 bias = *(const f32x4*)(AR.in[I_GLUB] + l * 512 + col);
; #pragma unroll
;         for (int m = 0; m < MT; ++m) { const int row = m * 16 + fr;
;             if (row < NROW) { const v2u yw = *(const LAS v2u*)(at + row * LDA + col * 2); const f32x4 z = acc[m][n] + bias;
;                 const float o0 = bflo(yw.x) * sigmoidf_(z.x), o1 = bfhi(yw.x) * sigmoidf_(z.y), o2 = bflo(yw.y) * sigmoidf_(z.z), o3 = bfhi(yw.y) * sigmoidf_(z.w);
;                 v2u o; o.x = pk2(o0, o1); o.y = pk2(o2, o3); *(v2u*)(CAT + (size_t)(row0 + row) * DM + 512 + col) = o; } } }
	v_mfma_f32_16x16x32_bf16 v[62:65], v[6:9], v[42:45], v[14:17]
	ds_read_b128 v[6:9], v137 offset:960
	v_mfma_f32_16x16x32_bf16 v[66:69], v[10:13], v[42:45], v[18:21]
	s_waitcnt vmcnt(1) lgkmcnt(0)
	v_mfma_f32_16x16x32_bf16 v[42:45], v[2:5], v[6:9], v[26:29]
	s_waitcnt vmcnt(0)
	v_mfma_f32_16x16x32_bf16 v[18:21], v[30:33], v[6:9], v[22:25]
	ds_read_b128 v[6:9], v137 offset:17600
	s_waitcnt lgkmcnt(0)
	v_mfma_f32_16x16x32_bf16 v[38:41], v[2:5], v[6:9], v[38:41]
	v_mfma_f32_16x16x32_bf16 v[14:17], v[30:33], v[6:9], v[34:37]
	ds_read_b128 v[6:9], v137 offset:34240
	s_waitcnt lgkmcnt(0)
	v_mfma_f32_16x16x32_bf16 v[34:37], v[2:5], v[6:9], v[46:49]
	s_nop 2
	ds_read_b128 v[46:49], v147 offset:960
	v_mfma_f32_16x16x32_bf16 v[10:13], v[30:33], v[6:9], v[50:53]
	ds_read_b128 v[6:9], v137 offset:50880
	s_waitcnt lgkmcnt(0)
	v_mfma_f32_16x16x32_bf16 v[26:29], v[2:5], v[6:9], v[54:57]
	v_mfma_f32_16x16x32_bf16 v[22:25], v[2:5], v[46:49], v[62:65]
	v_mfma_f32_16x16x32_bf16 v[2:5], v[30:33], v[46:49], v[66:69]
	v_or_b32_e32 v48, s4, v141
	v_ashrrev_i32_e32 v49, 31, v48
	v_lshl_add_u64 v[46:47], v[48:49], 2, s[0:1]
	v_mfma_f32_16x16x32_bf16 v[6:9], v[30:33], v[6:9], v[58:61]
	v_lshl_add_u32 v54, v48, 1, 0
	v_add_u32_e32 v50, v54, v140
	ds_read_b64 v[50:51], v50
	s_waitcnt lgkmcnt(0)
	v_lshlrev_b32_e32 v52, 16, v50
	v_and_b32_e32 v53, 0xffff0000, v50
	v_lshlrev_b32_e32 v50, 16, v51
	v_and_b32_e32 v51, 0xffff0000, v51
	s_waitcnt vmcnt(0)
	v_pk_add_f32 v[42:43], v[42:43], v[200:201]
	v_pk_add_f32 v[44:45], v[44:45], v[202:203]
	v_mul_f32_e32 v42, 0xbfb8aa3b, v42
	v_mul_f32_e32 v43, 0xbfb8aa3b, v43
	v_exp_f32_e32 v42, v42
	v_exp_f32_e32 v43, v43
	v_mul_f32_e32 v44, 0xbfb8aa3b, v44
	v_mul_f32_e32 v45, 0xbfb8aa3b, v45
	v_exp_f32_e32 v44, v44
	v_exp_f32_e32 v45, v45
	v_add_f32_e32 v42, 1.0, v42
	v_add_f32_e32 v43, 1.0, v43
	v_rcp_f32_e32 v42, v42
	v_rcp_f32_e32 v43, v43
	v_add_f32_e32 v44, 1.0, v44
	v_add_f32_e32 v45, 1.0, v45
	v_rcp_f32_e32 v44, v44
	v_rcp_f32_e32 v45, v45
	v_pk_mul_f32 v[42:43], v[42:43], v[52:53]
	v_pk_add_f32 v[38:39], v[38:39], v[200:201]
	v_pk_add_f32 v[40:41], v[40:41], v[202:203]
	v_pk_mul_f32 v[44:45], v[44:45], v[50:51]
	v_cvt_pk_bf16_f32 v50, v42, v43
	v_add_u32_e32 v42, s5, v138
	v_ashrrev_i32_e32 v43, 31, v42
	v_lshlrev_b64 v[42:43], 12, v[42:43]
	v_lshl_add_u64 v[42:43], s[90:91], 0, v[42:43]
	v_mul_f32_e32 v38, 0xbfb8aa3b, v38
	v_mul_f32_e32 v39, 0xbfb8aa3b, v39
	v_cvt_pk_bf16_f32 v51, v44, v45
	v_lshl_add_u64 v[42:43], v[42:43], 0, s[18:19]
	v_lshlrev_b64 v[44:45], 1, v[48:49]
	v_exp_f32_e32 v38, v38
	v_exp_f32_e32 v39, v39
	v_mul_f32_e32 v40, 0xbfb8aa3b, v40
	v_mul_f32_e32 v41, 0xbfb8aa3b, v41
	v_lshl_add_u64 v[52:53], v[42:43], 0, v[44:45]
	v_exp_f32_e32 v40, v40
	v_exp_f32_e32 v41, v41
	global_store_dwordx2 v[52:53], v[50:51], off
	v_add_u32_e32 v50, v54, v143
	ds_read_b64 v[52:53], v50
	v_add_f32_e32 v38, 1.0, v38
	v_add_f32_e32 v39, 1.0, v39
	v_rcp_f32_e32 v38, v38
	v_rcp_f32_e32 v39, v39
	v_add_f32_e32 v40, 1.0, v40
	v_add_f32_e32 v41, 1.0, v41
	v_rcp_f32_e32 v40, v40
	v_rcp_f32_e32 v41, v41
	s_waitcnt lgkmcnt(0)
	v_lshlrev_b32_e32 v54, 16, v52
	v_and_b32_e32 v55, 0xffff0000, v52
	v_pk_mul_f32 v[38:39], v[38:39], v[54:55]
	v_lshlrev_b32_e32 v52, 16, v53
	v_and_b32_e32 v53, 0xffff0000, v53
	v_pk_mul_f32 v[40:41], v[40:41], v[52:53]
	v_cvt_pk_bf16_f32 v52, v38, v39
	v_add_u32_e32 v38, s5, v142
	v_ashrrev_i32_e32 v39, 31, v38
	v_pk_add_f32 v[34:35], v[34:35], v[200:201]
	v_lshlrev_b64 v[38:39], 12, v[38:39]
	v_pk_add_f32 v[36:37], v[36:37], v[202:203]
	v_mul_f32_e32 v34, 0xbfb8aa3b, v34
	v_mul_f32_e32 v35, 0xbfb8aa3b, v35
	v_lshl_add_u64 v[38:39], s[90:91], 0, v[38:39]
	v_exp_f32_e32 v34, v34
	v_exp_f32_e32 v35, v35
	v_mul_f32_e32 v36, 0xbfb8aa3b, v36
	v_mul_f32_e32 v37, 0xbfb8aa3b, v37
	v_lshl_add_u64 v[38:39], v[38:39], 0, s[18:19]
	v_exp_f32_e32 v36, v36
	v_exp_f32_e32 v37, v37
	v_cvt_pk_bf16_f32 v53, v40, v41
	v_lshl_add_u64 v[40:41], v[38:39], 0, v[44:45]
	global_store_dwordx2 v[40:41], v[52:53], off
	ds_read_b64 v[40:41], v50 offset:16640
	v_add_f32_e32 v34, 1.0, v34
	v_add_f32_e32 v35, 1.0, v35
	v_rcp_f32_e32 v34, v34
	v_rcp_f32_e32 v35, v35
	v_add_f32_e32 v36, 1.0, v36
	v_add_f32_e32 v37, 1.0, v37
	v_rcp_f32_e32 v36, v36
	v_rcp_f32_e32 v37, v37
	s_waitcnt lgkmcnt(0)
	v_lshlrev_b32_e32 v52, 16, v40
	v_and_b32_e32 v53, 0xffff0000, v40
	v_pk_mul_f32 v[34:35], v[34:35], v[52:53]
	v_lshlrev_b32_e32 v40, 16, v41
	v_and_b32_e32 v41, 0xffff0000, v41
	v_pk_mul_f32 v[36:37], v[36:37], v[40:41]
	v_cvt_pk_bf16_f32 v40, v34, v35
	v_add_u32_e32 v34, s5, v144
	v_ashrrev_i32_e32 v35, 31, v34
	v_pk_add_f32 v[28:29], v[28:29], v[202:203]
	v_pk_add_f32 v[26:27], v[26:27], v[200:201]
	v_lshlrev_b64 v[34:35], 12, v[34:35]
	v_mul_f32_e32 v26, 0xbfb8aa3b, v26
	v_mul_f32_e32 v27, 0xbfb8aa3b, v27
	v_mul_f32_e32 v28, 0xbfb8aa3b, v28
	v_mul_f32_e32 v29, 0xbfb8aa3b, v29
	v_lshl_add_u64 v[34:35], s[90:91], 0, v[34:35]
	v_exp_f32_e32 v26, v26
	v_exp_f32_e32 v27, v27
	v_exp_f32_e32 v28, v28
	v_exp_f32_e32 v29, v29
	v_lshl_add_u64 v[34:35], v[34:35], 0, s[18:19]
	v_cvt_pk_bf16_f32 v41, v36, v37
	v_lshl_add_u64 v[36:37], v[34:35], 0, v[44:45]
	global_store_dwordx2 v[36:37], v[40:41], off
	ds_read_b64 v[36:37], v50 offset:33280
	v_add_f32_e32 v26, 1.0, v26
	v_add_f32_e32 v27, 1.0, v27
	v_add_f32_e32 v28, 1.0, v28
	v_add_f32_e32 v29, 1.0, v29
	v_rcp_f32_e32 v26, v26
	v_rcp_f32_e32 v27, v27
	v_rcp_f32_e32 v28, v28
	v_rcp_f32_e32 v29, v29
	s_waitcnt lgkmcnt(0)
	v_lshlrev_b32_e32 v40, 16, v36
	v_and_b32_e32 v41, 0xffff0000, v36
	v_lshlrev_b32_e32 v36, 16, v37
	v_and_b32_e32 v37, 0xffff0000, v37
	v_pk_mul_f32 v[26:27], v[26:27], v[40:41]
	v_pk_mul_f32 v[28:29], v[28:29], v[36:37]
	v_cvt_pk_bf16_f32 v26, v26, v27
	v_cvt_pk_bf16_f32 v27, v28, v29
	v_add_u32_e32 v28, s5, v145
	v_ashrrev_i32_e32 v29, 31, v28
	v_lshlrev_b64 v[28:29], 12, v[28:29]
	v_lshl_add_u64 v[28:29], s[90:91], 0, v[28:29]
	v_lshl_add_u64 v[28:29], v[28:29], 0, s[18:19]
	v_lshl_add_u64 v[36:37], v[28:29], 0, v[44:45]
	global_store_dwordx2 v[36:37], v[26:27], off
	v_add_u32_e32 v26, s5, v146
	v_ashrrev_i32_e32 v27, 31, v26
	s_and_saveexec_b64 s[4:5], s[40:41]
	s_cbranch_execz .LBB0_1681
; #define LAS __attribute__((address_space(3)))
; __device__ __forceinline__ unsigned pk2(float lo, float hi) { const f32x2cv v = {lo, hi}; return __builtin_bit_cast(unsigned, __builtin_convertvector(v, bf16x2cv)); }
; __device__ __forceinline__ float sigmoidf_(float x) { return __builtin_amdgcn_rcpf(1.0f + __expf(-x)); }
; __device__ __forceinline__ void glu_item(Frame& F, const Args& AR, int l, int item) {
;     ...
; #pragma unroll
;     for (int n = 0; n < 2; ++n) { const int col = colw + n * 16 + 4 * fq; const f32x4 bias = *(const f32x4*)(AR.in[I_GLUB] + l * 512 + col);
; #pragma unroll
;         for (int m = 0; m < MT; ++m) { const int row = m * 16 + fr;
;             if (row < NROW) { const v2u yw = *(const LAS v2u*)(at + row * LDA + col * 2); const f32x4 z = acc[m][n] + bias;
;                 const float o0 = bflo(yw.x) * sigmoidf_(z.x), o1 = bfhi(yw.x) * sigmoidf_(z.y), o2 = bflo(yw.y) * sigmoidf_(z.z), o3 = bfhi(yw.y) * sigmoidf_(z.w);
;                 v2u o; o.x = pk2(o0, o1); o.y = pk2(o2, o3); *(v2u*)(CAT + (size_t)(row0 + row) * DM + 512 + col) = o; } } }
	v_pk_add_f32 v[22:23], v[22:23], v[200:201]
	ds_read_b64 v[36:37], v50 offset:49920
	v_mul_f32_e32 v22, 0xbfb8aa3b, v22
	v_exp_f32_e32 v30, v22
	v_mul_f32_e32 v22, 0xbfb8aa3b, v23
	v_exp_f32_e32 v31, v22
	v_pk_add_f32 v[22:23], v[24:25], v[202:203]
	v_add_f32_e32 v24, 1.0, v30
	v_mul_f32_e32 v22, 0xbfb8aa3b, v22
	v_mul_f32_e32 v23, 0xbfb8aa3b, v23
	v_exp_f32_e32 v22, v22
	v_exp_f32_e32 v23, v23
	v_add_f32_e32 v25, 1.0, v31
	v_rcp_f32_e32 v24, v24
	v_rcp_f32_e32 v25, v25
	v_add_f32_e32 v22, 1.0, v22
	v_add_f32_e32 v23, 1.0, v23
	v_rcp_f32_e32 v22, v22
	v_rcp_f32_e32 v23, v23
	s_waitcnt lgkmcnt(0)
	v_lshlrev_b32_e32 v30, 16, v36
	v_and_b32_e32 v31, 0xffff0000, v36
	v_pk_mul_f32 v[24:25], v[24:25], v[30:31]
	v_lshlrev_b32_e32 v30, 16, v37
	v_and_b32_e32 v31, 0xffff0000, v37
	v_pk_mul_f32 v[22:23], v[22:23], v[30:31]
	v_cvt_pk_bf16_f32 v24, v24, v25
	v_cvt_pk_bf16_f32 v25, v22, v23
	v_lshlrev_b64 v[22:23], 12, v[26:27]
	v_lshl_add_u64 v[22:23], s[90:91], 0, v[22:23]
	v_lshl_add_u64 v[22:23], v[48:49], 1, v[22:23]
	v_add_co_u32_e32 v22, vcc, 0x3c500000, v22
	s_nop 1
	v_addc_co_u32_e32 v23, vcc, 0, v23, vcc
	global_store_dwordx2 v[22:23], v[24:25], off offset:1024
.LBB0_1681:
	s_or_b64 exec, exec, s[4:5]
	v_or_b32_e32 v30, 16, v48
	v_lshl_add_u32 v40, v30, 1, 0
	v_add_u32_e32 v32, v40, v140
	ds_read_b64 v[32:33], v32
	v_ashrrev_i32_e32 v31, 31, v30
	s_waitcnt lgkmcnt(0)
	v_lshlrev_b32_e32 v36, 16, v32
	v_and_b32_e32 v37, 0xffff0000, v32
	v_lshlrev_b32_e32 v32, 16, v33
	v_and_b32_e32 v33, 0xffff0000, v33
	v_pk_add_f32 v[18:19], v[18:19], v[204:205]
	v_pk_add_f32 v[20:21], v[20:21], v[206:207]
	v_mul_f32_e32 v18, 0xbfb8aa3b, v18
	v_mul_f32_e32 v19, 0xbfb8aa3b, v19
	v_exp_f32_e32 v18, v18
	v_exp_f32_e32 v19, v19
	v_mul_f32_e32 v20, 0xbfb8aa3b, v20
	v_mul_f32_e32 v21, 0xbfb8aa3b, v21
	v_exp_f32_e32 v20, v20
	v_exp_f32_e32 v21, v21
	v_add_f32_e32 v18, 1.0, v18
	v_add_f32_e32 v19, 1.0, v19
	v_rcp_f32_e32 v18, v18
	v_rcp_f32_e32 v19, v19
	v_add_f32_e32 v20, 1.0, v20
	v_add_f32_e32 v21, 1.0, v21
	v_rcp_f32_e32 v20, v20
	v_rcp_f32_e32 v21, v21
	v_pk_add_f32 v[16:17], v[16:17], v[206:207]
	v_pk_add_f32 v[14:15], v[14:15], v[204:205]
	v_pk_mul_f32 v[18:19], v[18:19], v[36:37]
	v_mul_f32_e32 v14, 0xbfb8aa3b, v14
	v_mul_f32_e32 v15, 0xbfb8aa3b, v15
	v_mul_f32_e32 v16, 0xbfb8aa3b, v16
	v_mul_f32_e32 v17, 0xbfb8aa3b, v17
	v_pk_mul_f32 v[20:21], v[20:21], v[32:33]
	v_cvt_pk_bf16_f32 v32, v18, v19
	v_lshlrev_b64 v[18:19], 1, v[30:31]
	v_exp_f32_e32 v14, v14
	v_exp_f32_e32 v15, v15
	v_exp_f32_e32 v16, v16
	v_exp_f32_e32 v17, v17
	v_cvt_pk_bf16_f32 v33, v20, v21
	v_lshl_add_u64 v[20:21], v[42:43], 0, v[18:19]
	global_store_dwordx2 v[20:21], v[32:33], off
	v_add_u32_e32 v20, v40, v143
	ds_read_b64 v[32:33], v20
	v_add_f32_e32 v14, 1.0, v14
	v_add_f32_e32 v15, 1.0, v15
	v_add_f32_e32 v16, 1.0, v16
	v_add_f32_e32 v17, 1.0, v17
	v_rcp_f32_e32 v14, v14
	v_rcp_f32_e32 v15, v15
	v_rcp_f32_e32 v16, v16
	v_rcp_f32_e32 v17, v17
	v_pk_add_f32 v[12:13], v[12:13], v[206:207]
	v_pk_add_f32 v[10:11], v[10:11], v[204:205]
	v_mul_f32_e32 v12, 0xbfb8aa3b, v12
	v_mul_f32_e32 v10, 0xbfb8aa3b, v10
	v_mul_f32_e32 v11, 0xbfb8aa3b, v11
	v_mul_f32_e32 v13, 0xbfb8aa3b, v13
	s_waitcnt lgkmcnt(0)
	v_lshlrev_b32_e32 v36, 16, v32
	v_and_b32_e32 v37, 0xffff0000, v32
	v_lshlrev_b32_e32 v32, 16, v33
	v_and_b32_e32 v33, 0xffff0000, v33
	v_exp_f32_e32 v10, v10
	v_exp_f32_e32 v11, v11
	v_exp_f32_e32 v12, v12
	v_exp_f32_e32 v13, v13
	v_pk_mul_f32 v[14:15], v[14:15], v[36:37]
	v_pk_mul_f32 v[16:17], v[16:17], v[32:33]
	v_cvt_pk_bf16_f32 v14, v14, v15
	v_cvt_pk_bf16_f32 v15, v16, v17
	v_lshl_add_u64 v[16:17], v[38:39], 0, v[18:19]
	global_store_dwordx2 v[16:17], v[14:15], off
	ds_read_b64 v[14:15], v20 offset:16640
	v_add_f32_e32 v10, 1.0, v10
	v_add_f32_e32 v11, 1.0, v11
	v_add_f32_e32 v12, 1.0, v12
	v_add_f32_e32 v13, 1.0, v13
	v_rcp_f32_e32 v10, v10
	v_rcp_f32_e32 v11, v11
	v_rcp_f32_e32 v12, v12
	v_rcp_f32_e32 v13, v13
	v_pk_add_f32 v[8:9], v[8:9], v[206:207]
	v_pk_add_f32 v[6:7], v[6:7], v[204:205]
	v_mul_f32_e32 v8, 0xbfb8aa3b, v8
	v_mul_f32_e32 v6, 0xbfb8aa3b, v6
	v_mul_f32_e32 v7, 0xbfb8aa3b, v7
	v_mul_f32_e32 v9, 0xbfb8aa3b, v9
	s_waitcnt lgkmcnt(0)
	v_lshlrev_b32_e32 v16, 16, v14
	v_and_b32_e32 v17, 0xffff0000, v14
	v_lshlrev_b32_e32 v14, 16, v15
	v_and_b32_e32 v15, 0xffff0000, v15
	v_exp_f32_e32 v6, v6
	v_exp_f32_e32 v7, v7
	v_exp_f32_e32 v8, v8
	v_exp_f32_e32 v9, v9
	v_pk_mul_f32 v[10:11], v[10:11], v[16:17]
	v_pk_mul_f32 v[12:13], v[12:13], v[14:15]
	v_cvt_pk_bf16_f32 v10, v10, v11
	v_cvt_pk_bf16_f32 v11, v12, v13
	v_lshl_add_u64 v[12:13], v[34:35], 0, v[18:19]
	global_store_dwordx2 v[12:13], v[10:11], off
	ds_read_b64 v[10:11], v20 offset:33280
	v_add_f32_e32 v6, 1.0, v6
	v_add_f32_e32 v7, 1.0, v7
	v_add_f32_e32 v8, 1.0, v8
	v_add_f32_e32 v9, 1.0, v9
	v_rcp_f32_e32 v6, v6
	v_rcp_f32_e32 v7, v7
	v_rcp_f32_e32 v8, v8
	v_rcp_f32_e32 v9, v9
	s_waitcnt lgkmcnt(0)
	v_lshlrev_b32_e32 v12, 16, v10
	v_and_b32_e32 v13, 0xffff0000, v10
	v_lshlrev_b32_e32 v10, 16, v11
	v_and_b32_e32 v11, 0xffff0000, v11
	v_pk_mul_f32 v[6:7], v[6:7], v[12:13]
	v_pk_mul_f32 v[8:9], v[8:9], v[10:11]
	v_cvt_pk_bf16_f32 v6, v6, v7
	v_cvt_pk_bf16_f32 v7, v8, v9
	v_lshl_add_u64 v[8:9], v[28:29], 0, v[18:19]
	global_store_dwordx2 v[8:9], v[6:7], off
	s_and_saveexec_b64 s[4:5], s[40:41]
	s_cbranch_execz .LBB0_1673
	v_pk_add_f32 v[2:3], v[2:3], v[204:205]
	ds_read_b64 v[6:7], v20 offset:49920
	v_mul_f32_e32 v2, 0xbfb8aa3b, v2
	v_exp_f32_e32 v8, v2
	v_mul_f32_e32 v2, 0xbfb8aa3b, v3
	v_exp_f32_e32 v9, v2
	v_pk_add_f32 v[2:3], v[4:5], v[206:207]
	v_add_f32_e32 v4, 1.0, v8
	v_mul_f32_e32 v2, 0xbfb8aa3b, v2
	v_mul_f32_e32 v3, 0xbfb8aa3b, v3
	v_exp_f32_e32 v2, v2
	v_exp_f32_e32 v3, v3
	v_add_f32_e32 v5, 1.0, v9
	v_rcp_f32_e32 v4, v4
	v_add_f32_e32 v2, 1.0, v2
	v_add_f32_e32 v3, 1.0, v3
	v_rcp_f32_e32 v5, v5
	v_rcp_f32_e32 v2, v2
	v_rcp_f32_e32 v3, v3
	s_waitcnt lgkmcnt(0)
	v_lshlrev_b32_e32 v8, 16, v6
	v_and_b32_e32 v9, 0xffff0000, v6
	v_lshlrev_b32_e32 v6, 16, v7
	v_and_b32_e32 v7, 0xffff0000, v7
	v_pk_mul_f32 v[4:5], v[4:5], v[8:9]
	v_pk_mul_f32 v[2:3], v[2:3], v[6:7]
	v_cvt_pk_bf16_f32 v4, v4, v5
	v_cvt_pk_bf16_f32 v5, v2, v3
	v_lshlrev_b64 v[2:3], 12, v[26:27]
	v_lshl_add_u64 v[2:3], s[90:91], 0, v[2:3]
	v_lshl_add_u64 v[2:3], v[30:31], 1, v[2:3]
	v_add_co_u32_e32 v2, vcc, 0x3c500000, v2
	s_nop 1
	v_addc_co_u32_e32 v3, vcc, 0, v3, vcc
	global_store_dwordx2 v[2:3], v[4:5], off offset:1024
	s_branch .LBB0_1673
